# P2 QK^T hand-scheduled: 8 per-lane LDS address constants + one uniform offset per key step (40 VALU instead of ~250), K-fragment reads 8 ahead through 9 rotating quads, the two score chains of a key s
# baseline (speedup 1.0000x reference)
; #define LAS __attribute__((address_space(3)))
; __device__ __forceinline__ void attn_compute(LAS unsigned char* lds, const bf16x8 (&qf)[4], const AttnUnit& u, bf16* og, float* lse) {
;     ...
;     const unsigned krow = 8 * (i15 >> 2) + (i15 & 3);
; #pragma unroll
;     for (int kk = 0; kk < 5; ++kk) {
;         const int ks = ks0 + kk;
;         bf16x8 kf[2][4];
; #pragma unroll
;         for (int T = 0; T < 2; ++T)
; #pragma unroll
;             for (int s = 0; s < 4; ++s) kf[T][s] = *(const LAS bf16x8*)(Ks + (off_b(32 * ks + krow + 4 * T, 4 * s + kg) ^ par));
; __global__ void __launch_bounds__(NTHREADS, 2) fwd_megakernel(Args args) {
;     ...
;         const int per = (NUNITS + G - 1) / G;
;         const int u0 = vcu * per, u1 = (u0 + per < NUNITS) ? u0 + per : NUNITS;
;         { const v4u z = {0u, 0u, 0u, 0u}; for (int i = threadIdx.x; i < 8192; i += NTHREADS) *(LAS v4u*)(lds + 16 * i) = z; }
;         asm volatile("s_waitcnt lgkmcnt(0)" ::: "memory"); __builtin_amdgcn_s_barrier(); asm volatile("" ::: "memory");
;         AttnRegs R;
;         if (u0 < u1) { const AttnUnit un = attn_decode(u0);
;             if (un.n > 0) { attn_issue(R, un, un.n - 1, false, PROJ, BIAS2); attn_commit(R, un.n - 1, false, lds); }
;             attn_issue(R, un, un.n, true, PROJ, BIAS2); }
.LBB0_145:
	s_add_u32 s0, s40, 0x3fc00000
	s_addc_u32 s1, s41, 0
	s_add_u32 s33, s40, 0xbc00000
	s_addc_u32 s46, s41, 0
	s_add_u32 s47, s38, 0x8000000
	s_addc_u32 s64, s39, 0
	s_add_i32 s4, s59, s10
	s_or_b32 s4, s4, s6
	s_ashr_i32 s5, s4, 31
	s_lshl_b64 s[4:5], s[4:5], 20
	v_lshrrev_b32_e32 v1, 2, v178
	s_add_u32 s4, s18, s4
	v_and_b32_e32 v33, 0xf0, v1
	s_addc_u32 s5, s19, s5
	v_or_b32_e32 v1, v33, v92
	s_add_i32 s8, s9, s8
	v_add_lshl_u32 v80, s8, v1, 8
	v_mov_b32_e32 v81, 0
	v_lshl_add_u64 v[2:3], s[4:5], 0, v[80:81]
	s_add_i32 s4, s58, s10
	v_lshrrev_b32_e32 v1, 1, v178
	s_ashr_i32 s5, s4, 31
	v_and_b32_e32 v34, 24, v1
	s_lshl_b64 s[4:5], s[4:5], 20
	v_lshlrev_b32_e32 v80, 1, v34
	v_add_u32_e32 v0, s9, v0
	s_add_u32 s4, s18, s4
	v_lshl_add_u64 v[2:3], v[2:3], 0, v[80:81]
	v_lshl_or_b32 v80, v0, 7, v91
	s_addc_u32 s5, s19, s5
	v_lshl_add_u64 v[12:13], v[80:81], 1, s[4:5]
	s_mov_b32 s65, 0x18006000
	v_add_co_u32_e32 v0, vcc, s65, v12
	s_mov_b32 s66, 0xc006000
	s_nop 0
	v_addc_co_u32_e32 v1, vcc, 0, v13, vcc
	global_load_dwordx4 v[48:51], v[2:3], off offset:192
	global_load_dwordx4 v[52:55], v[2:3], off offset:128
	global_load_dwordx4 v[56:59], v[2:3], off offset:64
	global_load_dwordx4 v[60:63], v[2:3], off
	v_add_co_u32_e32 v2, vcc, s66, v12
	s_mov_b32 s67, 0x18004000
	s_nop 0
	v_addc_co_u32_e32 v3, vcc, 0, v13, vcc
	v_add_co_u32_e32 v4, vcc, s67, v12
	s_mov_b32 s68, 0xc004000
	s_nop 0
	v_addc_co_u32_e32 v5, vcc, 0, v13, vcc
	v_add_co_u32_e32 v6, vcc, s68, v12
	s_mov_b32 s69, 0x18002000
	s_nop 0
	v_addc_co_u32_e32 v7, vcc, 0, v13, vcc
	v_add_co_u32_e32 v8, vcc, s69, v12
	s_mov_b32 s70, 0xc002000
	s_nop 0
	v_addc_co_u32_e32 v9, vcc, 0, v13, vcc
	s_lshl_b32 s4, s7, 3
	v_add_co_u32_e32 v10, vcc, s70, v12
	s_or_b32 s4, s4, s6
	s_movk_i32 s5, 0xc0
	v_addc_co_u32_e32 v11, vcc, 0, v13, vcc
	s_brev_b32 s71, 24
	s_mul_i32 s6, s4, 0xc0
	v_cmp_gt_u32_e64 s[4:5], s5, v178
	v_add_co_u32_e32 v14, vcc, s71, v12
	s_nop 0
	v_cndmask_b32_e64 v95, 0, v178, s[4:5]
	v_addc_co_u32_e32 v15, vcc, 0, v13, vcc
	s_brev_b32 s72, 48
	v_add_u32_e32 v36, s6, v95
	v_add_co_u32_e32 v12, vcc, s72, v12
	v_ashrrev_i32_e32 v37, 31, v36
	s_nop 0
	v_addc_co_u32_e32 v13, vcc, 0, v13, vcc
	v_lshl_add_u64 v[36:37], v[36:37], 2, s[56:57]
	global_load_dwordx4 v[28:31], v[0:1], off
	s_nop 0
	global_load_dwordx4 v[0:3], v[2:3], off
	s_nop 0
	global_load_dwordx4 v[16:19], v[4:5], off
	s_nop 0
	global_load_dwordx4 v[4:7], v[6:7], off
	s_nop 0
	global_load_dwordx4 v[20:23], v[8:9], off
	s_nop 0
	global_load_dwordx4 v[8:11], v[10:11], off
	s_nop 0
	global_load_dwordx4 v[24:27], v[14:15], off
	s_nop 0
	global_load_dwordx4 v[12:15], v[12:13], off
	v_lshlrev_b32_e32 v35, 2, v178
	global_load_dword v125, v[36:37], off
	s_add_i32 s6, 0, 0x20000
	v_add_u32_e32 v97, s6, v35
	v_and_b32_e32 v102, 12, v35
	v_lshrrev_b32_e32 v35, 1, v92
	v_bfe_u32 v99, v178, 4, 2
	v_and_b32_e32 v35, 2, v35
	v_or_b32_e32 v98, v33, v92
	v_lshrrev_b32_e32 v33, 2, v92
	v_bitop3_b32 v36, v35, v99, v102 bitop3:0x36
	v_or_b32_e32 v104, 4, v99
	v_lshlrev_b32_e32 v100, 3, v33
	v_lshlrev_b32_e32 v103, 4, v36
	v_bitop3_b32 v36, v35, v104, v102 bitop3:0x36
	v_or_b32_e32 v106, 8, v99
	v_or_b32_e32 v108, 12, v99
	v_lshl_or_b32 v111, v99, 3, v33
	v_lshlrev_b32_e32 v33, 1, v90
	v_lshlrev_b32_e32 v105, 4, v36
	v_bitop3_b32 v36, v35, v106, v102 bitop3:0x36
	v_bitop3_b32 v35, v35, v108, v102 bitop3:0x36
	v_and_b32_e32 v113, 12, v178
	v_and_b32_e32 v33, 2, v33
	v_lshlrev_b32_e32 v109, 4, v35
	v_bfe_u32 v112, v178, 1, 1
	v_or_b32_e32 v35, v33, v113
	v_and_b32_e32 v114, 8, v32
	v_or_b32_e32 v32, v35, v112
	v_or_b32_e32 v116, 2, v112
	v_lshlrev_b32_e32 v115, 4, v32
	v_bitop3_b32 v32, v33, v116, v113 bitop3:0x36
	v_or_b32_e32 v118, 4, v112
	v_lshlrev_b32_e32 v117, 4, v32
	v_bitop3_b32 v32, v33, v118, v113 bitop3:0x36
	v_or_b32_e32 v120, 6, v112
	v_lshlrev_b32_e32 v119, 4, v32
	v_bitop3_b32 v32, v33, v120, v113 bitop3:0x36
	v_or_b32_e32 v122, 8, v112
	v_lshlrev_b32_e32 v121, 4, v32
	v_bitop3_b32 v32, v33, v122, v113 bitop3:0x36
	v_or_b32_e32 v124, 10, v112
	v_lshlrev_b32_e32 v123, 4, v32
	v_bitop3_b32 v32, v33, v124, v113 bitop3:0x36
	v_or_b32_e32 v127, 12, v112
	v_lshlrev_b32_e32 v126, 4, v32
	v_bitop3_b32 v32, v33, v127, v113 bitop3:0x36
	v_or_b32_e32 v129, 14, v112
	v_lshlrev_b32_e32 v128, 4, v32
	v_bitop3_b32 v32, v33, v129, v113 bitop3:0x36
	v_lshlrev_b32_e32 v130, 4, v32
	v_lshlrev_b32_e32 v32, 2, v99
	v_lshlrev_b32_e32 v84, 1, v32
	v_mbcnt_lo_u32_b32 v32, -1, 0
	s_mov_b32 s9, 0
	v_or_b32_e32 v96, 0x4000, v93
	v_and_b32_e32 v101, 3, v178
	v_lshlrev_b32_e32 v107, 4, v36
	v_lshl_add_u32 v110, v99, 5, s6
	v_cmp_eq_u32_e64 s[6:7], 0, v99
	s_add_i32 s73, 0, 0x10000
	v_lshlrev_b32_e32 v82, 1, v34
	s_mov_b32 s74, 0xf149f2ca
	v_mov_b32_e32 v131, 0xf149f2ca
	v_mbcnt_hi_u32_b32 v132, -1, v32
	v_and_b32_e32 v245, 15, v178
	v_lshrrev_b32_e32 v254, 2, v245
	v_and_b32_e32 v255, 3, v245
	v_lshl_or_b32 v216, v254, 3, v255
	v_bfe_u32 v217, v178, 4, 2
	v_and_b32_e32 v218, 1, v254
	v_lshlrev_b32_e32 v218, 1, v218
	v_or_b32_e32 v219, 1, v218
	v_lshlrev_b32_e32 v220, 2, v255
	v_or_b32_e32 v218, v220, v218
	v_or_b32_e32 v219, v220, v219
	v_lshlrev_b32_e32 v221, 8, v216
	v_add_u32_e32 v222, 0x400, v221
	v_mov_b32_e32 v223, v217
	v_xor_b32_e32 v223, v223, v218
	v_lshl_or_b32 v208, v223, 4, v221
	v_or_b32_e32 v223, 4, v217
	v_xor_b32_e32 v223, v223, v218
	v_lshl_or_b32 v209, v223, 4, v221
	v_or_b32_e32 v223, 8, v217
	v_xor_b32_e32 v223, v223, v218
	v_lshl_or_b32 v210, v223, 4, v221
	v_or_b32_e32 v223, 12, v217
	v_xor_b32_e32 v223, v223, v218
	v_lshl_or_b32 v211, v223, 4, v221
	v_mov_b32_e32 v223, v217
	v_xor_b32_e32 v223, v223, v219
	v_lshl_or_b32 v212, v223, 4, v222
	v_or_b32_e32 v223, 4, v217
	v_xor_b32_e32 v223, v223, v219
	v_lshl_or_b32 v213, v223, 4, v222
	v_or_b32_e32 v223, 8, v217
	v_xor_b32_e32 v223, v223, v219
	v_lshl_or_b32 v214, v223, 4, v222
	v_or_b32_e32 v223, 12, v217
	v_xor_b32_e32 v223, v223, v219
	v_lshl_or_b32 v215, v223, 4, v222
	s_waitcnt vmcnt(0)
	s_branch .LBB0_147

; #define LAS __attribute__((address_space(3)))
; __device__ __forceinline__ void attn_compute(LAS unsigned char* lds, const bf16x8 (&qf)[4], const AttnUnit& u, bf16* og, float* lse) {
;     ...
;     const unsigned krow = 8 * (i15 >> 2) + (i15 & 3);
; #pragma unroll
;     for (int kk = 0; kk < 5; ++kk) {
;         const int ks = ks0 + kk;
;         bf16x8 kf[2][4];
; #pragma unroll
;         for (int T = 0; T < 2; ++T)
; #pragma unroll
;             for (int s = 0; s < 4; ++s) kf[T][s] = *(const LAS bf16x8*)(Ks + (off_b(32 * ks + krow + 4 * T, 4 * s + kg) ^ par));
; #pragma unroll
;         for (int T = 0; T < 2; ++T) {
;             f32x4 a = {0.f, 0.f, 0.f, 0.f};
; #pragma unroll
;             for (int s = 0; s < 4; ++s) a = __builtin_amdgcn_mfma_f32_16x16x32_bf16(kf[T][s], qf[s], a, 0, 0, 0);
;             sc[kk][T] = a;
;         }
;     }
.LBB0_151:
	s_bfe_u32 s76, s11, 0x30005
	s_sub_i32 s11, 5, s8
	s_lshr_b32 s11, s63, s11
	s_cmp_eq_u32 s10, 1
	s_cselect_b32 s30, s33, s47
	s_cselect_b32 s31, s46, s64
	s_cmp_eq_u32 s10, 0
	v_readfirstlane_b32 s85, v178
	s_cselect_b32 s61, s91, s31
	s_cselect_b32 s60, s90, s30
	s_lshr_b32 s86, s85, 2
	s_and_b32 s83, s86, 0x3fffffe0
	s_not_b32 s30, s63
	s_lshl_b32 s30, s30, 15
	s_and_b32 s77, s30, 0x8000
	s_lshl_b32 s99, s83, 8
	s_xor_b32 s92, s99, s77
	s_add_i32 s99, s99, 0x2000
	s_xor_b32 s93, s99, s77
	s_add_i32 s99, s99, 0x2000
	s_xor_b32 s94, s99, s77
	s_add_i32 s99, s99, 0x2000
	s_xor_b32 s97, s99, s77
	s_add_i32 s99, s99, 0x2000
	s_xor_b32 s98, s99, s77
	s_add_i32 s82, s83, 32
	s_add_i32 s80, s83, 64
	s_add_i32 s79, s83, 0x60
	s_add_i32 s78, s83, 0x80
	s_ashr_i32 s63, s62, 31
	s_and_b32 s54, s86, 0x3ffffff0
	s_lshl_b64 s[62:63], s[62:63], 12
	s_andn2_b32 s30, 16, s86
	s_cmp_eq_u32 s84, 0
	v_add_u32_e32 v245, s92, v208
	ds_read_b128 v[216:219], v245
	v_add_u32_e32 v254, s92, v212
	ds_read_b128 v[220:223], v254
	v_add_u32_e32 v255, s92, v209
	ds_read_b128 v[224:227], v255
	v_add_u32_e32 v245, s92, v213
	ds_read_b128 v[228:231], v245
	v_add_u32_e32 v254, s92, v210
	ds_read_b128 v[232:235], v254
	v_add_u32_e32 v255, s92, v214
	ds_read_b128 v[236:239], v255
	v_add_u32_e32 v245, s92, v211
	ds_read_b128 v[240:243], v245
	v_add_u32_e32 v254, s92, v215
	ds_read_b128 v[246:249], v254
	s_waitcnt lgkmcnt(7)
	v_mfma_f32_16x16x32_bf16 v[68:71], v[216:219], v[60:63], 0
	v_add_u32_e32 v255, s93, v208
	ds_read_b128 v[250:253], v255
	s_waitcnt lgkmcnt(7)
	v_mfma_f32_16x16x32_bf16 v[64:67], v[220:223], v[60:63], 0
	v_add_u32_e32 v245, s93, v212
	ds_read_b128 v[216:219], v245
	s_waitcnt lgkmcnt(7)
	v_mfma_f32_16x16x32_bf16 v[68:71], v[224:227], v[56:59], v[68:71]
	v_add_u32_e32 v254, s93, v209
	ds_read_b128 v[220:223], v254
	s_waitcnt lgkmcnt(7)
	v_mfma_f32_16x16x32_bf16 v[64:67], v[228:231], v[56:59], v[64:67]
	v_add_u32_e32 v255, s93, v213
	ds_read_b128 v[224:227], v255
	s_waitcnt lgkmcnt(7)
	v_mfma_f32_16x16x32_bf16 v[68:71], v[232:235], v[52:55], v[68:71]
	v_add_u32_e32 v245, s93, v210
	ds_read_b128 v[228:231], v245
	s_waitcnt lgkmcnt(7)
	v_mfma_f32_16x16x32_bf16 v[64:67], v[236:239], v[52:55], v[64:67]
	v_add_u32_e32 v254, s93, v214
	ds_read_b128 v[232:235], v254
	s_waitcnt lgkmcnt(7)
	v_mfma_f32_16x16x32_bf16 v[68:71], v[240:243], v[48:51], v[68:71]
	v_add_u32_e32 v255, s93, v211
	ds_read_b128 v[236:239], v255
	s_waitcnt lgkmcnt(7)
	v_mfma_f32_16x16x32_bf16 v[64:67], v[246:249], v[48:51], v[64:67]
	v_add_u32_e32 v245, s93, v215
	ds_read_b128 v[240:243], v245
	s_waitcnt lgkmcnt(7)
	v_mfma_f32_16x16x32_bf16 v[76:79], v[250:253], v[60:63], 0
	v_add_u32_e32 v254, s94, v208
	ds_read_b128 v[246:249], v254
	s_waitcnt lgkmcnt(7)
	v_mfma_f32_16x16x32_bf16 v[72:75], v[216:219], v[60:63], 0
	v_add_u32_e32 v255, s94, v212
	ds_read_b128 v[250:253], v255
	s_waitcnt lgkmcnt(7)
	v_mfma_f32_16x16x32_bf16 v[76:79], v[220:223], v[56:59], v[76:79]
	v_add_u32_e32 v245, s94, v209
	ds_read_b128 v[216:219], v245
	s_waitcnt lgkmcnt(7)
	v_mfma_f32_16x16x32_bf16 v[72:75], v[224:227], v[56:59], v[72:75]
	v_add_u32_e32 v254, s94, v213
	ds_read_b128 v[220:223], v254
	s_waitcnt lgkmcnt(7)
	v_mfma_f32_16x16x32_bf16 v[76:79], v[228:231], v[52:55], v[76:79]
	v_add_u32_e32 v255, s94, v210
	ds_read_b128 v[224:227], v255
	s_waitcnt lgkmcnt(7)
	v_mfma_f32_16x16x32_bf16 v[72:75], v[232:235], v[52:55], v[72:75]
	v_add_u32_e32 v245, s94, v214
	ds_read_b128 v[228:231], v245
	s_waitcnt lgkmcnt(7)
	v_mfma_f32_16x16x32_bf16 v[76:79], v[236:239], v[48:51], v[76:79]
	v_add_u32_e32 v254, s94, v211
	ds_read_b128 v[232:235], v254
	s_waitcnt lgkmcnt(7)
	v_mfma_f32_16x16x32_bf16 v[72:75], v[240:243], v[48:51], v[72:75]
	v_add_u32_e32 v255, s94, v215
	ds_read_b128 v[236:239], v255
	s_waitcnt lgkmcnt(7)
	v_mfma_f32_16x16x32_bf16 v[138:141], v[246:249], v[60:63], 0
	v_add_u32_e32 v245, s97, v208
	ds_read_b128 v[240:243], v245
	s_waitcnt lgkmcnt(7)
	v_mfma_f32_16x16x32_bf16 v[134:137], v[250:253], v[60:63], 0
	v_add_u32_e32 v254, s97, v212
	ds_read_b128 v[246:249], v254
	s_waitcnt lgkmcnt(7)
	v_mfma_f32_16x16x32_bf16 v[138:141], v[216:219], v[56:59], v[138:141]
	v_add_u32_e32 v255, s97, v209
	ds_read_b128 v[250:253], v255
	s_waitcnt lgkmcnt(7)
	v_mfma_f32_16x16x32_bf16 v[134:137], v[220:223], v[56:59], v[134:137]
	v_add_u32_e32 v245, s97, v213
	ds_read_b128 v[216:219], v245
	s_waitcnt lgkmcnt(7)
	v_mfma_f32_16x16x32_bf16 v[138:141], v[224:227], v[52:55], v[138:141]
	v_add_u32_e32 v254, s97, v210
	ds_read_b128 v[220:223], v254
	s_waitcnt lgkmcnt(7)
	v_mfma_f32_16x16x32_bf16 v[134:137], v[228:231], v[52:55], v[134:137]
	v_add_u32_e32 v255, s97, v214
	ds_read_b128 v[224:227], v255
	s_waitcnt lgkmcnt(7)
	v_mfma_f32_16x16x32_bf16 v[138:141], v[232:235], v[48:51], v[138:141]
	v_add_u32_e32 v245, s97, v211
	ds_read_b128 v[228:231], v245
	s_waitcnt lgkmcnt(7)
	v_mfma_f32_16x16x32_bf16 v[134:137], v[236:239], v[48:51], v[134:137]
	v_add_u32_e32 v254, s97, v215
	ds_read_b128 v[232:235], v254
	s_waitcnt lgkmcnt(7)
	v_mfma_f32_16x16x32_bf16 v[146:149], v[240:243], v[60:63], 0
	v_add_u32_e32 v255, s98, v208
	ds_read_b128 v[236:239], v255
	s_waitcnt lgkmcnt(7)
	v_mfma_f32_16x16x32_bf16 v[142:145], v[246:249], v[60:63], 0
	v_add_u32_e32 v245, s98, v212
	ds_read_b128 v[240:243], v245
	s_waitcnt lgkmcnt(7)
	v_mfma_f32_16x16x32_bf16 v[146:149], v[250:253], v[56:59], v[146:149]
	v_add_u32_e32 v254, s98, v209
	ds_read_b128 v[246:249], v254
	s_waitcnt lgkmcnt(7)
	v_mfma_f32_16x16x32_bf16 v[142:145], v[216:219], v[56:59], v[142:145]
	v_add_u32_e32 v255, s98, v213
	ds_read_b128 v[250:253], v255
	s_waitcnt lgkmcnt(7)
; #define LAS __attribute__((address_space(3)))
; __device__ __forceinline__ void attn_compute(LAS unsigned char* lds, const bf16x8 (&qf)[4], const AttnUnit& u, bf16* og, float* lse) {
;     ...
;     for (int kk = 0; kk < 5; ++kk) {
;         const int ks = ks0 + kk;
;         bf16x8 kf[2][4];
; #pragma unroll
;         for (int T = 0; T < 2; ++T)
; #pragma unroll
;             for (int s = 0; s < 4; ++s) kf[T][s] = *(const LAS bf16x8*)(Ks + (off_b(32 * ks + krow + 4 * T, 4 * s + kg) ^ par));
; #pragma unroll
;         for (int T = 0; T < 2; ++T) {
;             f32x4 a = {0.f, 0.f, 0.f, 0.f};
; #pragma unroll
;             for (int s = 0; s < 4; ++s) a = __builtin_amdgcn_mfma_f32_16x16x32_bf16(kf[T][s], qf[s], a, 0, 0, 0);
;             sc[kk][T] = a;
;         }
;     }
;     float tb[5][2][4];
;     { const LAS float* tp = tab + (31 - 16 * (w & 1) - i15 + 8 * kg);
; #pragma unroll
;       for (int kk = 0; kk < 5; ++kk)
; #pragma unroll
;           for (int T = 0; T < 2; ++T)
; #pragma unroll
;               for (int jj = 0; jj < 4; ++jj) tb[kk][T][jj] = tp[32 * kk + 4 * T + jj]; }
;     const float SCL = 0.08838834764831845f * 1.4426950408889634f;
;     float mx = -1e30f;
; #pragma unroll
;     for (int kk = 0; kk < 5; ++kk) {
;         const bool dead = (n == 0) && (ks0 + kk < 4);
; #pragma unroll
;         for (int T = 0; T < 2; ++T)
; #pragma unroll
;             for (int jj = 0; jj < 4; ++jj) { float v = sc[kk][T][jj] * SCL + tb[kk][T][jj]; v = dead ? -1e30f : v; sc[kk][T][jj] = v; mx = fmaxf(mx, v); }
;     }
	v_mfma_f32_16x16x32_bf16 v[146:149], v[220:223], v[52:55], v[146:149]
	v_add_u32_e32 v245, s98, v210
	ds_read_b128 v[216:219], v245
	s_waitcnt lgkmcnt(7)
	v_mfma_f32_16x16x32_bf16 v[142:145], v[224:227], v[52:55], v[142:145]
	v_add_u32_e32 v254, s98, v214
	ds_read_b128 v[220:223], v254
	s_waitcnt lgkmcnt(7)
	v_mfma_f32_16x16x32_bf16 v[146:149], v[228:231], v[48:51], v[146:149]
	v_add_u32_e32 v255, s98, v211
	ds_read_b128 v[224:227], v255
	s_waitcnt lgkmcnt(7)
	v_mfma_f32_16x16x32_bf16 v[142:145], v[232:235], v[48:51], v[142:145]
	v_add_u32_e32 v245, s98, v215
	ds_read_b128 v[228:231], v245
	s_waitcnt lgkmcnt(7)
	v_mfma_f32_16x16x32_bf16 v[154:157], v[236:239], v[60:63], 0
	s_waitcnt lgkmcnt(6)
	v_mfma_f32_16x16x32_bf16 v[158:161], v[240:243], v[60:63], 0
	s_waitcnt lgkmcnt(5)
	v_mfma_f32_16x16x32_bf16 v[154:157], v[246:249], v[56:59], v[154:157]
	s_waitcnt lgkmcnt(4)
	v_mfma_f32_16x16x32_bf16 v[158:161], v[250:253], v[56:59], v[158:161]
	s_waitcnt lgkmcnt(3)
	v_mfma_f32_16x16x32_bf16 v[154:157], v[216:219], v[52:55], v[154:157]
	s_waitcnt lgkmcnt(2)
	v_mfma_f32_16x16x32_bf16 v[158:161], v[220:223], v[52:55], v[158:161]
	s_waitcnt lgkmcnt(1)
	v_mfma_f32_16x16x32_bf16 v[154:157], v[224:227], v[48:51], v[154:157]
	s_waitcnt lgkmcnt(0)
	v_mfma_f32_16x16x32_bf16 v[52:55], v[228:231], v[48:51], v[158:161]
	v_sub_u32_e32 v48, s30, v92
	v_lshl_add_u32 v48, v48, 2, v110
	s_cselect_b64 s[30:31], -1, 0
	s_cmpk_lt_u32 s85, 0x200
	ds_read2_b32 v[56:57], v48 offset0:15 offset1:16
	ds_read2_b32 v[58:59], v48 offset0:17 offset1:18
	ds_read2_b32 v[60:61], v48 offset0:19 offset1:20
	ds_read2_b32 v[62:63], v48 offset0:21 offset1:22
	ds_read2_b32 v[150:151], v48 offset0:47 offset1:48
	ds_read2_b32 v[152:153], v48 offset0:49 offset1:50
	ds_read2_b32 v[158:159], v48 offset0:51 offset1:52
	ds_read2_b32 v[160:161], v48 offset0:53 offset1:54
	ds_read2_b32 v[162:163], v48 offset0:79 offset1:80
	ds_read2_b32 v[164:165], v48 offset0:81 offset1:82
	ds_read2_b32 v[166:167], v48 offset0:83 offset1:84
	ds_read2_b32 v[168:169], v48 offset0:85 offset1:86
	ds_read2_b32 v[170:171], v48 offset0:111 offset1:112
	ds_read2_b32 v[172:173], v48 offset0:113 offset1:114
	ds_read2_b32 v[174:175], v48 offset0:115 offset1:116
	ds_read2_b32 v[176:177], v48 offset0:117 offset1:118
	ds_read2_b32 v[88:89], v48 offset0:143 offset1:144
	ds_read2_b32 v[86:87], v48 offset0:145 offset1:146
	ds_read2_b32 v[50:51], v48 offset0:147 offset1:148
	ds_read2_b32 v[48:49], v48 offset0:149 offset1:150
	s_cselect_b64 s[86:87], -1, 0
	s_waitcnt lgkmcnt(14)
	v_fmamk_f32 v56, v68, 0x3e0293ee, v56
	s_and_b64 vcc, s[30:31], s[86:87]
	v_fmac_f32_e32 v57, 0x3e0293ee, v69
	v_cndmask_b32_e32 v56, v56, v131, vcc
	v_cndmask_b32_e32 v57, v57, v131, vcc
	v_fmamk_f32 v58, v70, 0x3e0293ee, v58
	v_fmac_f32_e32 v59, 0x3e0293ee, v71
	v_max3_f32 v68, v56, s74, v57
	v_cndmask_b32_e32 v58, v58, v131, vcc
	v_cndmask_b32_e32 v59, v59, v131, vcc
	v_fmamk_f32 v60, v64, 0x3e0293ee, v60
	v_fmac_f32_e32 v61, 0x3e0293ee, v65
	s_cmpk_lt_u32 s85, 0x180
	v_max3_f32 v68, v68, v58, v59
	v_cndmask_b32_e32 v60, v60, v131, vcc
	v_cndmask_b32_e32 v61, v61, v131, vcc
	v_fmamk_f32 v62, v66, 0x3e0293ee, v62
	v_fmac_f32_e32 v63, 0x3e0293ee, v67
	s_cselect_b64 s[86:87], -1, 0
	v_max3_f32 v64, v68, v60, v61
	v_cndmask_b32_e32 v62, v62, v131, vcc
	v_cndmask_b32_e32 v63, v63, v131, vcc
	v_fmamk_f32 v65, v76, 0x3e0293ee, v150
	s_and_b64 vcc, s[30:31], s[86:87]
	v_fmac_f32_e32 v151, 0x3e0293ee, v77
	v_max3_f32 v64, v64, v62, v63
	v_cndmask_b32_e32 v69, v65, v131, vcc
	v_cndmask_b32_e32 v70, v151, v131, vcc
	v_fmamk_f32 v65, v78, 0x3e0293ee, v152
	v_fmac_f32_e32 v153, 0x3e0293ee, v79
	v_max3_f32 v64, v64, v69, v70
	v_cndmask_b32_e32 v71, v65, v131, vcc
	v_cndmask_b32_e32 v76, v153, v131, vcc
	s_waitcnt lgkmcnt(13)
	v_fmamk_f32 v65, v72, 0x3e0293ee, v158
	v_fmac_f32_e32 v159, 0x3e0293ee, v73
	s_cmpk_lt_u32 s85, 0x100
	v_max3_f32 v64, v64, v71, v76
	v_cndmask_b32_e32 v72, v65, v131, vcc
	v_cndmask_b32_e32 v73, v159, v131, vcc
	s_waitcnt lgkmcnt(12)
	v_fmamk_f32 v65, v74, 0x3e0293ee, v160
	v_fmac_f32_e32 v161, 0x3e0293ee, v75
	s_cselect_b64 s[86:87], -1, 0
	v_max3_f32 v64, v64, v72, v73
	v_cndmask_b32_e32 v74, v65, v131, vcc
	v_cndmask_b32_e32 v75, v161, v131, vcc
	s_waitcnt lgkmcnt(11)
	v_fmamk_f32 v65, v138, 0x3e0293ee, v162
	s_and_b64 vcc, s[30:31], s[86:87]
	v_fmac_f32_e32 v163, 0x3e0293ee, v139
	v_max3_f32 v64, v64, v74, v75
	v_cndmask_b32_e32 v77, v65, v131, vcc
	v_cndmask_b32_e32 v78, v163, v131, vcc
	s_waitcnt lgkmcnt(10)
	v_fmamk_f32 v65, v140, 0x3e0293ee, v164
	v_fmac_f32_e32 v165, 0x3e0293ee, v141
	v_max3_f32 v64, v64, v77, v78
	v_cndmask_b32_e32 v79, v65, v131, vcc
	v_cndmask_b32_e32 v83, v165, v131, vcc
	s_waitcnt lgkmcnt(9)
	v_fmamk_f32 v65, v134, 0x3e0293ee, v166
	v_fmac_f32_e32 v167, 0x3e0293ee, v135
	s_cmpk_lt_u32 s85, 0x80
	v_max3_f32 v64, v64, v79, v83
	v_cndmask_b32_e32 v85, v65, v131, vcc
	v_cndmask_b32_e32 v133, v167, v131, vcc
	s_waitcnt lgkmcnt(8)
	v_fmamk_f32 v65, v136, 0x3e0293ee, v168
	v_fmac_f32_e32 v169, 0x3e0293ee, v137
	s_cselect_b64 s[84:85], -1, 0
	v_max3_f32 v64, v64, v85, v133
	v_cndmask_b32_e32 v134, v65, v131, vcc
	v_cndmask_b32_e32 v135, v169, v131, vcc
	s_waitcnt lgkmcnt(7)
	v_fmamk_f32 v65, v146, 0x3e0293ee, v170
	s_and_b64 vcc, s[30:31], s[84:85]
	v_fmac_f32_e32 v171, 0x3e0293ee, v147
	v_max3_f32 v64, v64, v134, v135
	v_cndmask_b32_e32 v136, v65, v131, vcc
	v_cndmask_b32_e32 v137, v171, v131, vcc
	s_waitcnt lgkmcnt(6)
	v_fmamk_f32 v65, v148, 0x3e0293ee, v172
	v_fmac_f32_e32 v173, 0x3e0293ee, v149
	v_max3_f32 v64, v64, v136, v137
	v_cndmask_b32_e32 v138, v65, v131, vcc
	v_cndmask_b32_e32 v139, v173, v131, vcc
	s_waitcnt lgkmcnt(5)
; __device__ __forceinline__ unsigned cvtpk(float lo, float hi) { f32x2_t v = {lo, hi}; bf16x2_t b = __builtin_convertvector(v, bf16x2_t); return __builtin_bit_cast(unsigned, b); }
; #define ATT_VLOAD(kk_, buf_) do { const unsigned r0_ = 32 * (ks0 + (kk_)) + 8 * kg + q4; _Pragma("unroll") for (int c = 0; c < 8; ++c) { \
;         vlo[buf_][c] = vtr(vbase + ((off_b(r0_, 2 * c + (p4 >> 1)) + 8 * (p4 & 1)) ^ par)); vhi[buf_][c] = vtr(vbase + ((off_b(r0_ + 4, 2 * c + (p4 >> 1)) + 8 * (p4 & 1)) ^ par)); } } while (0)
; __device__ __forceinline__ void attn_compute(LAS unsigned char* lds, const bf16x8 (&qf)[4], const AttnUnit& u, bf16* og, float* lse) {
;     ...
;             for (int jj = 0; jj < 4; ++jj) { float v = sc[kk][T][jj] * SCL + tb[kk][T][jj]; v = dead ? -1e30f : v; sc[kk][T][jj] = v; mx = fmaxf(mx, v); }
;     }
;     mx = fmaxf(mx, __shfl_xor(mx, 16)); mx = fmaxf(mx, __shfl_xor(mx, 32));
;     float l = 0.f;
;     bf16x8 pf[5];
; #pragma unroll
;     for (int kk = 0; kk < 5; ++kk) {
;         float e[8];
; #pragma unroll
;         for (int T = 0; T < 2; ++T)
; #pragma unroll
;             for (int jj = 0; jj < 4; ++jj) { const float p = __builtin_amdgcn_exp2f(sc[kk][T][jj] - mx); e[4 * T + jj] = p; l += p; }
;         v4u pw; pw.x = cvtpk(e[0], e[1]); pw.y = cvtpk(e[2], e[3]); pw.z = cvtpk(e[4], e[5]); pw.w = cvtpk(e[6], e[7]);
;         pf[kk] = __builtin_bit_cast(bf16x8, pw);
;     }
;     l += __shfl_xor(l, 16); l += __shfl_xor(l, 32);
;     f32x4 o[8];
; #pragma unroll
;     for (int c = 0; c < 8; ++c) o[c] = (f32x4){0.f, 0.f, 0.f, 0.f};
;     const unsigned vbase = (unsigned)(uintptr_t)Vs;
;     const unsigned q4 = (lane & 15) >> 2, p4 = lane & 3;
;     s16x4 vlo[2][8], vhi[2][8];
;     ...
;     ATT_VLOAD(0, 0);
; #pragma unroll
;     for (int kk = 0; kk < 5; ++kk) {
;         if (kk < 4) ATT_VLOAD(kk + 1, (kk + 1) & 1);
	v_fmamk_f32 v65, v142, 0x3e0293ee, v174
	v_fmac_f32_e32 v175, 0x3e0293ee, v143
	v_max3_f32 v64, v64, v138, v139
	v_cndmask_b32_e32 v140, v65, v131, vcc
	v_cndmask_b32_e32 v141, v175, v131, vcc
	s_waitcnt lgkmcnt(4)
	v_fmamk_f32 v65, v144, 0x3e0293ee, v176
	v_fmac_f32_e32 v177, 0x3e0293ee, v145
	v_max3_f32 v64, v64, v140, v141
	v_cndmask_b32_e32 v142, v65, v131, vcc
	v_cndmask_b32_e32 v143, v177, v131, vcc
	v_max3_f32 v64, v64, v142, v143
	s_waitcnt lgkmcnt(3)
	v_fmamk_f32 v88, v154, 0x3e0293ee, v88
	v_fmac_f32_e32 v89, 0x3e0293ee, v155
	s_waitcnt lgkmcnt(0)
	v_fmamk_f32 v48, v54, 0x3e0293ee, v48
	v_and_b32_e32 v54, 64, v132
	v_max3_f32 v64, v64, v88, v89
	v_fmamk_f32 v86, v156, 0x3e0293ee, v86
	v_fmac_f32_e32 v87, 0x3e0293ee, v157
	v_fmac_f32_e32 v51, 0x3e0293ee, v53
	v_xor_b32_e32 v53, 16, v132
	v_add_u32_e32 v54, 64, v54
	v_max3_f32 v64, v64, v86, v87
	v_fmamk_f32 v50, v52, 0x3e0293ee, v50
	v_cmp_lt_i32_e32 vcc, v53, v54
	v_max3_f32 v52, v64, v50, v51
	v_fmac_f32_e32 v49, 0x3e0293ee, v55
	v_cndmask_b32_e32 v53, v132, v53, vcc
	v_max3_f32 v52, v52, v48, v49
	v_lshlrev_b32_e32 v144, 2, v53
	ds_bpermute_b32 v53, v144, v52
	s_or_b32 s62, s62, s11
	s_waitcnt lgkmcnt(0)
	v_max_f32_e32 v53, v53, v53
	v_max_f32_e32 v52, v52, v53
	v_xor_b32_e32 v53, 32, v132
	v_cmp_lt_i32_e32 vcc, v53, v54
	v_or_b32_e32 v54, s81, v92
	v_add_u32_e32 v80, s54, v54
	v_cndmask_b32_e32 v53, v132, v53, vcc
	v_lshlrev_b32_e32 v145, 2, v53
	ds_bpermute_b32 v53, v145, v52
	s_waitcnt lgkmcnt(0)
	v_max_f32_e32 v53, v53, v53
	v_max_f32_e32 v68, v52, v53
	v_sub_f32_e32 v52, v56, v68
	v_exp_f32_e32 v52, v52
	v_sub_f32_e32 v53, v57, v68
	v_exp_f32_e32 v53, v53
	v_sub_f32_e32 v54, v58, v68
	v_exp_f32_e32 v54, v54
	v_sub_f32_e32 v55, v59, v68
	v_exp_f32_e32 v55, v55
	v_sub_f32_e32 v57, v60, v68
	v_add_f32_e32 v56, 0, v52
	v_exp_f32_e32 v57, v57
	v_sub_f32_e32 v58, v61, v68
	v_add_f32_e32 v56, v53, v56
	v_exp_f32_e32 v58, v58
	v_sub_f32_e32 v59, v62, v68
	v_add_f32_e32 v56, v54, v56
	v_exp_f32_e32 v59, v59
	v_sub_f32_e32 v60, v63, v68
	v_add_f32_e32 v56, v55, v56
	v_exp_f32_e32 v60, v60
	v_cvt_pk_bf16_f32 v64, v52, v53
	v_sub_f32_e32 v52, v69, v68
	v_add_f32_e32 v56, v57, v56
	v_exp_f32_e32 v52, v52
	v_sub_f32_e32 v53, v70, v68
	v_add_f32_e32 v56, v58, v56
	v_cvt_pk_bf16_f32 v65, v54, v55
	v_exp_f32_e32 v53, v53
	v_sub_f32_e32 v54, v71, v68
	v_add_f32_e32 v56, v59, v56
	v_exp_f32_e32 v54, v54
	v_sub_f32_e32 v55, v76, v68
	v_add_f32_e32 v56, v60, v56
	v_cvt_pk_bf16_f32 v66, v57, v58
	v_exp_f32_e32 v55, v55
	v_sub_f32_e32 v57, v72, v68
	v_add_f32_e32 v56, v52, v56
	v_exp_f32_e32 v57, v57
	v_sub_f32_e32 v58, v73, v68
	v_cvt_pk_bf16_f32 v67, v59, v60
	v_add_f32_e32 v56, v53, v56
	v_exp_f32_e32 v58, v58
	v_sub_f32_e32 v59, v74, v68
	v_add_f32_e32 v56, v54, v56
	v_exp_f32_e32 v59, v59
	v_sub_f32_e32 v60, v75, v68
	v_add_f32_e32 v56, v55, v56
	v_exp_f32_e32 v63, v60
	v_cvt_pk_bf16_f32 v60, v52, v53
	v_sub_f32_e32 v52, v77, v68
	v_add_f32_e32 v56, v57, v56
	v_exp_f32_e32 v52, v52
	v_sub_f32_e32 v53, v78, v68
	v_add_f32_e32 v56, v58, v56
	v_cvt_pk_bf16_f32 v61, v54, v55
	v_exp_f32_e32 v53, v53
	v_sub_f32_e32 v54, v79, v68
	v_add_f32_e32 v56, v59, v56
	v_exp_f32_e32 v54, v54
	v_sub_f32_e32 v55, v83, v68
	v_add_f32_e32 v56, v63, v56
	v_cvt_pk_bf16_f32 v62, v57, v58
	v_exp_f32_e32 v55, v55
	v_sub_f32_e32 v57, v85, v68
	v_add_f32_e32 v56, v52, v56
	v_exp_f32_e32 v58, v57
	v_sub_f32_e32 v57, v133, v68
	v_cvt_pk_bf16_f32 v63, v59, v63
	v_add_f32_e32 v56, v53, v56
	v_exp_f32_e32 v59, v57
	v_sub_f32_e32 v57, v134, v68
	v_add_f32_e32 v56, v54, v56
	v_exp_f32_e32 v69, v57
	v_sub_f32_e32 v57, v135, v68
	v_add_f32_e32 v56, v55, v56
	v_exp_f32_e32 v70, v57
	v_add_f32_e32 v56, v58, v56
	v_add_f32_e32 v56, v59, v56
	v_add_f32_e32 v56, v69, v56
	v_add_f32_e32 v71, v70, v56
	v_cvt_pk_bf16_f32 v56, v52, v53
	v_sub_f32_e32 v52, v136, v68
	v_exp_f32_e32 v52, v52
	v_sub_f32_e32 v53, v137, v68
	v_cvt_pk_bf16_f32 v57, v54, v55
	v_exp_f32_e32 v53, v53
	v_sub_f32_e32 v54, v138, v68
	v_exp_f32_e32 v54, v54
	v_sub_f32_e32 v55, v139, v68
	v_cvt_pk_bf16_f32 v58, v58, v59
	v_cvt_pk_bf16_f32 v59, v69, v70
	v_exp_f32_e32 v55, v55
	v_add_f32_e32 v69, v52, v71
	v_sub_f32_e32 v70, v140, v68
	v_sub_f32_e32 v71, v141, v68
	v_exp_f32_e32 v70, v70
	v_exp_f32_e32 v71, v71
	v_add_f32_e32 v69, v53, v69
	v_sub_f32_e32 v72, v142, v68
	v_sub_f32_e32 v73, v143, v68
	v_add_f32_e32 v69, v54, v69
	v_exp_f32_e32 v72, v72
	v_exp_f32_e32 v73, v73
	v_add_f32_e32 v69, v55, v69
	v_add_f32_e32 v69, v70, v69
	v_cvt_pk_bf16_f32 v52, v52, v53
	v_cvt_pk_bf16_f32 v53, v54, v55
	v_cvt_pk_bf16_f32 v54, v70, v71
	v_sub_f32_e32 v70, v88, v68
	v_add_f32_e32 v69, v71, v69
	v_exp_f32_e32 v70, v70
	v_sub_f32_e32 v71, v89, v68
	v_add_f32_e32 v69, v72, v69
	v_cvt_pk_bf16_f32 v55, v72, v73
	v_exp_f32_e32 v71, v71
	v_sub_f32_e32 v72, v86, v68
	v_add_f32_e32 v69, v73, v69
	v_exp_f32_e32 v72, v72
	v_sub_f32_e32 v73, v87, v68
	v_exp_f32_e32 v73, v73
	v_sub_f32_e32 v50, v50, v68
	v_add_f32_e32 v69, v70, v69
	v_exp_f32_e32 v50, v50
	v_sub_f32_e32 v51, v51, v68
	v_add_f32_e32 v69, v71, v69
	v_exp_f32_e32 v51, v51
	v_sub_f32_e32 v48, v48, v68
	v_add_f32_e32 v69, v72, v69
	v_exp_f32_e32 v74, v48
	v_sub_f32_e32 v48, v49, v68
	v_add_f32_e32 v69, v73, v69
	v_exp_f32_e32 v75, v48
	v_add_f32_e32 v48, v50, v69
	v_add_f32_e32 v48, v51, v48
	v_add_f32_e32 v48, v74, v48
	v_add_f32_e32 v69, v75, v48
	v_cvt_pk_bf16_f32 v48, v70, v71
	v_or_b32_e32 v71, s83, v111
	v_lshl_or_b32 v83, v71, 8, v114
	v_or_b32_e32 v71, 4, v71
	v_bitop3_b32 v133, v83, s77, v121 bitop3:0x36
	v_bfe_u32 v85, v71, 2, 2
	v_add_u32_e32 v133, s73, v133
	ds_read_b64_tr_b16 v[134:135], v133
	v_bitop3_b32 v133, v85, v120, v113 bitop3:0x36
	v_lshl_or_b32 v71, v71, 8, v114
	v_lshlrev_b32_e32 v133, 4, v133
	v_bitop3_b32 v133, v133, s77, v71 bitop3:0x36
	v_add_u32_e32 v133, s73, v133
	ds_read_b64_tr_b16 v[136:137], v133
	v_bitop3_b32 v133, v83, s77, v123 bitop3:0x36
	v_add_u32_e32 v133, s73, v133
	ds_read_b64_tr_b16 v[138:139], v133
	v_bitop3_b32 v133, v85, v122, v113 bitop3:0x36
	v_lshlrev_b32_e32 v133, 4, v133
	v_bitop3_b32 v133, v133, s77, v71 bitop3:0x36
	v_add_u32_e32 v133, s73, v133
	ds_bpermute_b32 v76, v144, v69
	ds_read_b64_tr_b16 v[140:141], v133
	v_bitop3_b32 v133, v83, s77, v126 bitop3:0x36
	v_add_u32_e32 v133, s73, v133
	ds_read_b64_tr_b16 v[142:143], v133
	v_bitop3_b32 v133, v85, v124, v113 bitop3:0x36
	v_lshlrev_b32_e32 v133, 4, v133
	v_bitop3_b32 v133, v133, s77, v71 bitop3:0x36
	s_waitcnt lgkmcnt(2)
; #define ATT_VLOAD(kk_, buf_) do { const unsigned r0_ = 32 * (ks0 + (kk_)) + 8 * kg + q4; _Pragma("unroll") for (int c = 0; c < 8; ++c) { \
;         vlo[buf_][c] = vtr(vbase + ((off_b(r0_, 2 * c + (p4 >> 1)) + 8 * (p4 & 1)) ^ par)); vhi[buf_][c] = vtr(vbase + ((off_b(r0_ + 4, 2 * c + (p4 >> 1)) + 8 * (p4 & 1)) ^ par)); } } while (0)
; __device__ __forceinline__ void attn_compute(LAS unsigned char* lds, const bf16x8 (&qf)[4], const AttnUnit& u, bf16* og, float* lse) {
;     ...
;     l += __shfl_xor(l, 16); l += __shfl_xor(l, 32);
;     f32x4 o[8];
; #pragma unroll
;     for (int c = 0; c < 8; ++c) o[c] = (f32x4){0.f, 0.f, 0.f, 0.f};
;     const unsigned vbase = (unsigned)(uintptr_t)Vs;
;     const unsigned q4 = (lane & 15) >> 2, p4 = lane & 3;
;     s16x4 vlo[2][8], vhi[2][8];
;     ...
;     ATT_VLOAD(0, 0);
; #pragma unroll
;     for (int kk = 0; kk < 5; ++kk) {
;         if (kk < 4) ATT_VLOAD(kk + 1, (kk + 1) & 1);
; #pragma unroll
;         for (int c = 0; c < 8; ++c) {
;             const s16x4 lo = vlo[kk & 1][c], hi = vhi[kk & 1][c];
;             const bf16x8 vf = (bf16x8){lo[0], lo[1], lo[2], lo[3], hi[0], hi[1], hi[2], hi[3]};
;             o[c] = __builtin_amdgcn_mfma_f32_16x16x32_bf16(vf, pf[kk], o[c], 0, 0, 0);
	v_add_f32_e32 v69, v69, v76
	v_add_u32_e32 v133, s73, v133
	v_cvt_pk_bf16_f32 v49, v72, v73
	ds_bpermute_b32 v70, v145, v69
	v_bitop3_b32 v72, v83, s77, v115 bitop3:0x36
	v_bitop3_b32 v76, v83, s77, v117 bitop3:0x36
	v_bitop3_b32 v86, v83, s77, v119 bitop3:0x36
	ds_read_b64_tr_b16 v[144:145], v133
	v_bitop3_b32 v133, v83, s77, v128 bitop3:0x36
	v_bitop3_b32 v83, v83, s77, v130 bitop3:0x36
	v_add_u32_e32 v133, s73, v133
	v_add_u32_e32 v83, s73, v83
	v_cvt_pk_bf16_f32 v50, v50, v51
	v_cvt_pk_bf16_f32 v51, v74, v75
	v_bitop3_b32 v74, v85, v112, v113 bitop3:0x36
	v_bitop3_b32 v78, v85, v116, v113 bitop3:0x36
	v_bitop3_b32 v88, v85, v118, v113 bitop3:0x36
	ds_read_b64_tr_b16 v[146:147], v133
	v_bitop3_b32 v133, v85, v127, v113 bitop3:0x36
	ds_read_b64_tr_b16 v[150:151], v83
	v_bitop3_b32 v83, v85, v129, v113 bitop3:0x36
	v_lshlrev_b32_e32 v74, 4, v74
	v_lshlrev_b32_e32 v78, 4, v78
	v_lshlrev_b32_e32 v88, 4, v88
	v_lshlrev_b32_e32 v133, 4, v133
	v_lshlrev_b32_e32 v83, 4, v83
	v_bitop3_b32 v74, v74, s77, v71 bitop3:0x36
	v_bitop3_b32 v78, v78, s77, v71 bitop3:0x36
	v_bitop3_b32 v88, v88, s77, v71 bitop3:0x36
	v_bitop3_b32 v133, v133, s77, v71 bitop3:0x36
	v_bitop3_b32 v71, v83, s77, v71 bitop3:0x36
	v_add_u32_e32 v71, s73, v71
	ds_read_b64_tr_b16 v[152:153], v71
	v_or_b32_e32 v71, s82, v111
	v_add_u32_e32 v133, s73, v133
	v_lshl_or_b32 v83, v71, 8, v114
	ds_read_b64_tr_b16 v[148:149], v133
	v_or_b32_e32 v71, 4, v71
	v_bitop3_b32 v133, v83, s77, v115 bitop3:0x36
	v_bfe_u32 v85, v71, 2, 2
	v_add_u32_e32 v133, s73, v133
	ds_read_b64_tr_b16 v[154:155], v133
	v_bitop3_b32 v133, v85, v112, v113 bitop3:0x36
	v_lshl_or_b32 v71, v71, 8, v114
	v_lshlrev_b32_e32 v133, 4, v133
	v_bitop3_b32 v133, v133, s77, v71 bitop3:0x36
	v_add_u32_e32 v133, s73, v133
	ds_read_b64_tr_b16 v[156:157], v133
	v_bitop3_b32 v133, v83, s77, v117 bitop3:0x36
	v_add_u32_e32 v133, s73, v133
	ds_read_b64_tr_b16 v[158:159], v133
	v_bitop3_b32 v133, v85, v116, v113 bitop3:0x36
	v_lshlrev_b32_e32 v133, 4, v133
	v_bitop3_b32 v133, v133, s77, v71 bitop3:0x36
	v_add_u32_e32 v133, s73, v133
	ds_read_b64_tr_b16 v[160:161], v133
	v_bitop3_b32 v133, v83, s77, v119 bitop3:0x36
	v_add_u32_e32 v133, s73, v133
	ds_read_b64_tr_b16 v[162:163], v133
	v_bitop3_b32 v133, v85, v118, v113 bitop3:0x36
	v_lshlrev_b32_e32 v133, 4, v133
	v_bitop3_b32 v133, v133, s77, v71 bitop3:0x36
	v_add_u32_e32 v133, s73, v133
	ds_read_b64_tr_b16 v[164:165], v133
	v_bitop3_b32 v133, v83, s77, v121 bitop3:0x36
	v_add_u32_e32 v133, s73, v133
	ds_read_b64_tr_b16 v[166:167], v133
	v_bitop3_b32 v133, v85, v120, v113 bitop3:0x36
	v_lshlrev_b32_e32 v133, 4, v133
	v_bitop3_b32 v133, v133, s77, v71 bitop3:0x36
	v_add_u32_e32 v133, s73, v133
	ds_read_b64_tr_b16 v[168:169], v133
	v_bitop3_b32 v133, v83, s77, v123 bitop3:0x36
	v_add_u32_e32 v133, s73, v133
	ds_read_b64_tr_b16 v[170:171], v133
	v_bitop3_b32 v133, v85, v122, v113 bitop3:0x36
	v_lshlrev_b32_e32 v133, 4, v133
	v_bitop3_b32 v133, v133, s77, v71 bitop3:0x36
	v_add_u32_e32 v133, s73, v133
	ds_read_b64_tr_b16 v[172:173], v133
	v_bitop3_b32 v133, v83, s77, v126 bitop3:0x36
	v_add_u32_e32 v133, s73, v133
	ds_read_b64_tr_b16 v[174:175], v133
	v_bitop3_b32 v133, v85, v124, v113 bitop3:0x36
	v_lshlrev_b32_e32 v133, 4, v133
	v_bitop3_b32 v133, v133, s77, v71 bitop3:0x36
	v_add_u32_e32 v133, s73, v133
	v_add_u32_e32 v72, s73, v72
	v_add_u32_e32 v74, s73, v74
	v_add_u32_e32 v76, s73, v76
	v_add_u32_e32 v78, s73, v78
	v_add_u32_e32 v86, s73, v86
	v_add_u32_e32 v88, s73, v88
	ds_read_b64_tr_b16 v[176:177], v133
	v_bitop3_b32 v133, v83, s77, v128 bitop3:0x36
	v_bitop3_b32 v83, v83, s77, v130 bitop3:0x36
	ds_read_b64_tr_b16 v[72:73], v72
	ds_read_b64_tr_b16 v[74:75], v74
	ds_read_b64_tr_b16 v[76:77], v76
	ds_read_b64_tr_b16 v[78:79], v78
	ds_read_b64_tr_b16 v[86:87], v86
	ds_read_b64_tr_b16 v[88:89], v88
	v_add_u32_e32 v133, s73, v133
	v_add_u32_e32 v83, s73, v83
	ds_read_b64_tr_b16 v[180:181], v133
	v_bitop3_b32 v133, v85, v127, v113 bitop3:0x36
	ds_read_b64_tr_b16 v[184:185], v83
	v_bitop3_b32 v83, v85, v129, v113 bitop3:0x36
	v_lshlrev_b32_e32 v133, 4, v133
	v_lshlrev_b32_e32 v83, 4, v83
	v_bitop3_b32 v133, v133, s77, v71 bitop3:0x36
	v_bitop3_b32 v71, v83, s77, v71 bitop3:0x36
	v_add_u32_e32 v71, s73, v71
	ds_read_b64_tr_b16 v[186:187], v71
	v_or_b32_e32 v71, s80, v111
	v_add_u32_e32 v133, s73, v133
	v_lshl_or_b32 v83, v71, 8, v114
	ds_read_b64_tr_b16 v[182:183], v133
	v_or_b32_e32 v71, 4, v71
	v_bitop3_b32 v133, v83, s77, v115 bitop3:0x36
	v_bfe_u32 v85, v71, 2, 2
	v_add_u32_e32 v133, s73, v133
	s_waitcnt lgkmcnt(8)
	v_mfma_f32_16x16x32_bf16 v[72:75], v[72:75], v[64:67], 0
	v_lshl_or_b32 v71, v71, 8, v114
	s_waitcnt lgkmcnt(6)
	v_mfma_f32_16x16x32_bf16 v[76:79], v[76:79], v[64:67], 0
	s_waitcnt lgkmcnt(4)
; #define ATT_VLOAD(kk_, buf_) do { const unsigned r0_ = 32 * (ks0 + (kk_)) + 8 * kg + q4; _Pragma("unroll") for (int c = 0; c < 8; ++c) { \
;         vlo[buf_][c] = vtr(vbase + ((off_b(r0_, 2 * c + (p4 >> 1)) + 8 * (p4 & 1)) ^ par)); vhi[buf_][c] = vtr(vbase + ((off_b(r0_ + 4, 2 * c + (p4 >> 1)) + 8 * (p4 & 1)) ^ par)); } } while (0)
; __device__ __forceinline__ void attn_compute(LAS unsigned char* lds, const bf16x8 (&qf)[4], const AttnUnit& u, bf16* og, float* lse) {
;     ...
;     ATT_VLOAD(0, 0);
; #pragma unroll
;     for (int kk = 0; kk < 5; ++kk) {
;         if (kk < 4) ATT_VLOAD(kk + 1, (kk + 1) & 1);
; #pragma unroll
;         for (int c = 0; c < 8; ++c) {
;             const s16x4 lo = vlo[kk & 1][c], hi = vhi[kk & 1][c];
;             const bf16x8 vf = (bf16x8){lo[0], lo[1], lo[2], lo[3], hi[0], hi[1], hi[2], hi[3]};
;             o[c] = __builtin_amdgcn_mfma_f32_16x16x32_bf16(vf, pf[kk], o[c], 0, 0, 0);
;         }
;     }
	v_mfma_f32_16x16x32_bf16 v[86:89], v[86:89], v[64:67], 0
	v_mfma_f32_16x16x32_bf16 v[134:137], v[134:137], v[64:67], 0
	v_mfma_f32_16x16x32_bf16 v[138:141], v[138:141], v[64:67], 0
	v_mfma_f32_16x16x32_bf16 v[142:145], v[142:145], v[64:67], 0
	v_mfma_f32_16x16x32_bf16 v[146:149], v[146:149], v[64:67], 0
	v_mfma_f32_16x16x32_bf16 v[64:67], v[150:153], v[64:67], 0
	ds_read_b64_tr_b16 v[150:151], v133
	v_bitop3_b32 v133, v85, v112, v113 bitop3:0x36
	v_lshlrev_b32_e32 v133, 4, v133
	v_bitop3_b32 v133, v133, s77, v71 bitop3:0x36
	v_add_u32_e32 v133, s73, v133
	ds_read_b64_tr_b16 v[152:153], v133
	v_bitop3_b32 v133, v83, s77, v117 bitop3:0x36
	v_add_u32_e32 v133, s73, v133
	ds_read_b64_tr_b16 v[188:189], v133
	v_bitop3_b32 v133, v85, v116, v113 bitop3:0x36
	v_lshlrev_b32_e32 v133, 4, v133
	v_bitop3_b32 v133, v133, s77, v71 bitop3:0x36
	v_add_u32_e32 v133, s73, v133
	ds_read_b64_tr_b16 v[190:191], v133
	v_bitop3_b32 v133, v83, s77, v119 bitop3:0x36
	v_add_u32_e32 v133, s73, v133
	ds_read_b64_tr_b16 v[192:193], v133
	v_bitop3_b32 v133, v85, v118, v113 bitop3:0x36
	v_lshlrev_b32_e32 v133, 4, v133
	v_bitop3_b32 v133, v133, s77, v71 bitop3:0x36
	v_add_u32_e32 v133, s73, v133
	ds_read_b64_tr_b16 v[194:195], v133
	v_bitop3_b32 v133, v83, s77, v121 bitop3:0x36
	v_add_u32_e32 v133, s73, v133
	ds_read_b64_tr_b16 v[196:197], v133
	v_bitop3_b32 v133, v85, v120, v113 bitop3:0x36
	v_lshlrev_b32_e32 v133, 4, v133
	v_bitop3_b32 v133, v133, s77, v71 bitop3:0x36
	v_add_u32_e32 v133, s73, v133
	ds_read_b64_tr_b16 v[198:199], v133
	v_bitop3_b32 v133, v83, s77, v123 bitop3:0x36
	v_add_u32_e32 v133, s73, v133
	ds_read_b64_tr_b16 v[200:201], v133
	v_bitop3_b32 v133, v85, v122, v113 bitop3:0x36
	v_lshlrev_b32_e32 v133, 4, v133
	v_bitop3_b32 v133, v133, s77, v71 bitop3:0x36
	v_add_u32_e32 v133, s73, v133
	ds_read_b64_tr_b16 v[202:203], v133
	v_bitop3_b32 v133, v83, s77, v126 bitop3:0x36
	v_add_u32_e32 v133, s73, v133
	ds_read_b64_tr_b16 v[204:205], v133
	v_bitop3_b32 v133, v85, v124, v113 bitop3:0x36
	v_lshlrev_b32_e32 v133, 4, v133
	v_bitop3_b32 v133, v133, s77, v71 bitop3:0x36
	v_add_u32_e32 v133, s73, v133
	ds_read_b64_tr_b16 v[206:207], v133
	v_bitop3_b32 v133, v83, s77, v128 bitop3:0x36
	v_bitop3_b32 v83, v83, s77, v130 bitop3:0x36
	v_add_u32_e32 v133, s73, v133
	v_add_u32_e32 v83, s73, v83
	v_mfma_f32_16x16x32_bf16 v[72:75], v[154:157], v[60:63], v[72:75]
	ds_read_b64_tr_b16 v[154:155], v133
	v_bitop3_b32 v133, v85, v127, v113 bitop3:0x36
	v_lshlrev_b32_e32 v133, 4, v133
	v_mfma_f32_16x16x32_bf16 v[76:79], v[158:161], v[60:63], v[76:79]
	ds_read_b64_tr_b16 v[158:159], v83
	v_bitop3_b32 v83, v85, v129, v113 bitop3:0x36
	v_lshlrev_b32_e32 v83, 4, v83
	v_bitop3_b32 v133, v133, s77, v71 bitop3:0x36
	v_bitop3_b32 v71, v83, s77, v71 bitop3:0x36
	v_mfma_f32_16x16x32_bf16 v[86:89], v[162:165], v[60:63], v[86:89]
	v_add_u32_e32 v71, s73, v71
	v_add_u32_e32 v133, s73, v133
	ds_read_b64_tr_b16 v[160:161], v71
	v_mfma_f32_16x16x32_bf16 v[134:137], v[166:169], v[60:63], v[134:137]
	ds_read_b64_tr_b16 v[156:157], v133
	v_mfma_f32_16x16x32_bf16 v[138:141], v[170:173], v[60:63], v[138:141]
	v_mfma_f32_16x16x32_bf16 v[142:145], v[174:177], v[60:63], v[142:145]
	s_waitcnt lgkmcnt(14)
	v_mfma_f32_16x16x32_bf16 v[146:149], v[180:183], v[60:63], v[146:149]
	v_mfma_f32_16x16x32_bf16 v[60:63], v[184:187], v[60:63], v[64:67]
	s_nop 2
	v_or_b32_e32 v64, s79, v111
	v_lshl_or_b32 v71, v64, 8, v114
	v_or_b32_e32 v64, 4, v64
	v_bitop3_b32 v133, v71, s77, v117 bitop3:0x36
	v_bfe_u32 v83, v64, 2, 2
	v_add_u32_e32 v133, s73, v133
	ds_read_b64_tr_b16 v[162:163], v133
	v_bitop3_b32 v133, v83, v116, v113 bitop3:0x36
	v_lshl_or_b32 v85, v64, 8, v114
	v_lshlrev_b32_e32 v133, 4, v133
	v_bitop3_b32 v133, v133, s77, v85 bitop3:0x36
	v_add_u32_e32 v133, s73, v133
	ds_read_b64_tr_b16 v[164:165], v133
	v_bitop3_b32 v133, v71, s77, v119 bitop3:0x36
	v_add_u32_e32 v133, s73, v133
	ds_read_b64_tr_b16 v[166:167], v133
	v_bitop3_b32 v133, v83, v118, v113 bitop3:0x36
	v_lshlrev_b32_e32 v133, 4, v133
	v_bitop3_b32 v133, v133, s77, v85 bitop3:0x36
	v_add_u32_e32 v133, s73, v133
	ds_read_b64_tr_b16 v[168:169], v133
	v_bitop3_b32 v133, v71, s77, v121 bitop3:0x36
	v_add_u32_e32 v133, s73, v133
	ds_read_b64_tr_b16 v[170:171], v133
	v_bitop3_b32 v133, v83, v120, v113 bitop3:0x36
	v_lshlrev_b32_e32 v133, 4, v133
	v_bitop3_b32 v133, v133, s77, v85 bitop3:0x36
	v_add_u32_e32 v133, s73, v133
	ds_read_b64_tr_b16 v[172:173], v133
	v_bitop3_b32 v133, v71, s77, v123 bitop3:0x36
	v_add_u32_e32 v133, s73, v133
	ds_read_b64_tr_b16 v[174:175], v133
	v_bitop3_b32 v133, v83, v122, v113 bitop3:0x36
	v_lshlrev_b32_e32 v133, 4, v133
	v_bitop3_b32 v133, v133, s77, v85 bitop3:0x36
	v_add_u32_e32 v133, s73, v133
	ds_read_b64_tr_b16 v[176:177], v133
	v_bitop3_b32 v133, v71, s77, v126 bitop3:0x36
	v_add_u32_e32 v133, s73, v133
	ds_read_b64_tr_b16 v[180:181], v133
	v_bitop3_b32 v133, v83, v124, v113 bitop3:0x36
	v_lshlrev_b32_e32 v133, 4, v133
	v_bitop3_b32 v133, v133, s77, v85 bitop3:0x36
	v_add_u32_e32 v133, s73, v133
	v_bitop3_b32 v64, v71, s77, v115 bitop3:0x36
	ds_read_b64_tr_b16 v[182:183], v133
	v_bitop3_b32 v133, v71, s77, v128 bitop3:0x36
	v_bitop3_b32 v71, v71, s77, v130 bitop3:0x36
	v_add_u32_e32 v71, s73, v71
	v_add_u32_e32 v133, s73, v133
	ds_read_b64_tr_b16 v[184:185], v71
	v_bitop3_b32 v71, v83, v129, v113 bitop3:0x36
	v_mfma_f32_16x16x32_bf16 v[72:75], v[150:153], v[56:59], v[72:75]
	ds_read_b64_tr_b16 v[150:151], v133
	v_bitop3_b32 v133, v83, v127, v113 bitop3:0x36
	v_lshlrev_b32_e32 v71, 4, v71
	v_lshlrev_b32_e32 v133, 4, v133
	v_bitop3_b32 v71, v71, s77, v85 bitop3:0x36
	v_bitop3_b32 v66, v83, v112, v113 bitop3:0x36
	s_waitcnt lgkmcnt(14)
; #define ATT_VLOAD(kk_, buf_) do { const unsigned r0_ = 32 * (ks0 + (kk_)) + 8 * kg + q4; _Pragma("unroll") for (int c = 0; c < 8; ++c) { \
;         vlo[buf_][c] = vtr(vbase + ((off_b(r0_, 2 * c + (p4 >> 1)) + 8 * (p4 & 1)) ^ par)); vhi[buf_][c] = vtr(vbase + ((off_b(r0_ + 4, 2 * c + (p4 >> 1)) + 8 * (p4 & 1)) ^ par)); } } while (0)
; __device__ __forceinline__ void attn_compute(LAS unsigned char* lds, const bf16x8 (&qf)[4], const AttnUnit& u, bf16* og, float* lse) {
;     ...
;     ATT_VLOAD(0, 0);
; #pragma unroll
;     for (int kk = 0; kk < 5; ++kk) {
;         if (kk < 4) ATT_VLOAD(kk + 1, (kk + 1) & 1);
; #pragma unroll
;         for (int c = 0; c < 8; ++c) {
;             const s16x4 lo = vlo[kk & 1][c], hi = vhi[kk & 1][c];
;             const bf16x8 vf = (bf16x8){lo[0], lo[1], lo[2], lo[3], hi[0], hi[1], hi[2], hi[3]};
;             o[c] = __builtin_amdgcn_mfma_f32_16x16x32_bf16(vf, pf[kk], o[c], 0, 0, 0);
;         }
;     }
	v_mfma_f32_16x16x32_bf16 v[76:79], v[188:191], v[56:59], v[76:79]
	v_bitop3_b32 v133, v133, s77, v85 bitop3:0x36
	v_add_u32_e32 v71, s73, v71
	v_lshlrev_b32_e32 v66, 4, v66
	v_mfma_f32_16x16x32_bf16 v[86:89], v[192:195], v[56:59], v[86:89]
	v_add_u32_e32 v133, s73, v133
	ds_read_b64_tr_b16 v[186:187], v71
	v_bitop3_b32 v66, v66, s77, v85 bitop3:0x36
	v_mfma_f32_16x16x32_bf16 v[134:137], v[196:199], v[56:59], v[134:137]
	ds_read_b64_tr_b16 v[152:153], v133
	v_add_u32_e32 v64, s73, v64
	v_add_u32_e32 v66, s73, v66
	v_mfma_f32_16x16x32_bf16 v[138:141], v[200:203], v[56:59], v[138:141]
	ds_read_b64_tr_b16 v[64:65], v64
	ds_read_b64_tr_b16 v[66:67], v66
	v_mfma_f32_16x16x32_bf16 v[142:145], v[204:207], v[56:59], v[142:145]
	s_waitcnt lgkmcnt(14)
	v_mfma_f32_16x16x32_bf16 v[146:149], v[154:157], v[56:59], v[146:149]
	v_mfma_f32_16x16x32_bf16 v[56:59], v[158:161], v[56:59], v[60:63]
	s_nop 2
	v_or_b32_e32 v60, s78, v111
	v_lshl_or_b32 v71, v60, 8, v114
	v_or_b32_e32 v60, 4, v60
	v_bitop3_b32 v133, v71, s77, v117 bitop3:0x36
	v_bfe_u32 v83, v60, 2, 2
	v_add_u32_e32 v133, s73, v133
	ds_read_b64_tr_b16 v[154:155], v133
	v_bitop3_b32 v133, v83, v116, v113 bitop3:0x36
	v_lshl_or_b32 v85, v60, 8, v114
	v_lshlrev_b32_e32 v133, 4, v133
	v_bitop3_b32 v133, v133, s77, v85 bitop3:0x36
	v_add_u32_e32 v133, s73, v133
	ds_read_b64_tr_b16 v[156:157], v133
	v_bitop3_b32 v133, v71, s77, v119 bitop3:0x36
	v_add_u32_e32 v133, s73, v133
	ds_read_b64_tr_b16 v[158:159], v133
	v_bitop3_b32 v133, v83, v118, v113 bitop3:0x36
	v_lshlrev_b32_e32 v133, 4, v133
	v_bitop3_b32 v133, v133, s77, v85 bitop3:0x36
	v_add_u32_e32 v133, s73, v133
	s_waitcnt lgkmcnt(3)
	v_mfma_f32_16x16x32_bf16 v[64:67], v[64:67], v[52:55], v[72:75]
	ds_read_b64_tr_b16 v[160:161], v133
	v_bitop3_b32 v62, v83, v112, v113 bitop3:0x36
	v_lshlrev_b32_e32 v62, 4, v62
	v_bitop3_b32 v72, v71, s77, v121 bitop3:0x36
	v_add_u32_e32 v133, s73, v72
	v_mfma_f32_16x16x32_bf16 v[72:75], v[162:165], v[52:55], v[76:79]
	v_bitop3_b32 v60, v71, s77, v115 bitop3:0x36
	v_bitop3_b32 v62, v62, s77, v85 bitop3:0x36
	v_add_u32_e32 v60, s73, v60
	ds_read_b64_tr_b16 v[76:77], v133
	v_bitop3_b32 v133, v71, s77, v123 bitop3:0x36
	v_add_u32_e32 v133, s73, v133
	ds_read_b64_tr_b16 v[162:163], v133
	v_bitop3_b32 v133, v83, v122, v113 bitop3:0x36
	v_lshlrev_b32_e32 v133, 4, v133
	v_bitop3_b32 v133, v133, s77, v85 bitop3:0x36
	v_add_u32_e32 v133, s73, v133
	v_add_u32_e32 v62, s73, v62
	ds_read_b64_tr_b16 v[164:165], v133
	v_bitop3_b32 v133, v71, s77, v126 bitop3:0x36
	ds_read_b64_tr_b16 v[60:61], v60
	ds_read_b64_tr_b16 v[62:63], v62
	v_add_u32_e32 v133, s73, v133
	v_mfma_f32_16x16x32_bf16 v[146:149], v[150:153], v[52:55], v[146:149]
	ds_read_b64_tr_b16 v[150:151], v133
	v_bitop3_b32 v133, v83, v124, v113 bitop3:0x36
	v_bitop3_b32 v78, v83, v120, v113 bitop3:0x36
	v_mfma_f32_16x16x32_bf16 v[86:89], v[166:169], v[52:55], v[86:89]
	v_lshlrev_b32_e32 v78, 4, v78
	v_bitop3_b32 v78, v78, s77, v85 bitop3:0x36
	v_add_u32_e32 v78, s73, v78
	v_mfma_f32_16x16x32_bf16 v[134:137], v[170:173], v[52:55], v[134:137]
	ds_read_b64_tr_b16 v[78:79], v78
	v_mfma_f32_16x16x32_bf16 v[138:141], v[174:177], v[52:55], v[138:141]
	v_mfma_f32_16x16x32_bf16 v[142:145], v[180:183], v[52:55], v[142:145]
	v_mfma_f32_16x16x32_bf16 v[56:59], v[184:187], v[52:55], v[56:59]
	v_lshlrev_b32_e32 v52, 4, v133
	v_bitop3_b32 v52, v52, s77, v85 bitop3:0x36
	v_bitop3_b32 v54, v83, v127, v113 bitop3:0x36
	v_add_u32_e32 v52, s73, v52
	v_lshlrev_b32_e32 v54, 4, v54
	ds_read_b64_tr_b16 v[152:153], v52
	v_bitop3_b32 v52, v71, s77, v128 bitop3:0x36
	v_bitop3_b32 v54, v54, s77, v85 bitop3:0x36
	v_add_u32_e32 v52, s73, v52
	v_add_u32_e32 v54, s73, v54
	ds_read_b64_tr_b16 v[52:53], v52
	ds_read_b64_tr_b16 v[54:55], v54
	v_bitop3_b32 v71, v71, s77, v130 bitop3:0x36
	v_add_u32_e32 v71, s73, v71
	s_waitcnt lgkmcnt(5)
; __device__ __forceinline__ unsigned cvtpk(float lo, float hi) { f32x2_t v = {lo, hi}; bf16x2_t b = __builtin_convertvector(v, bf16x2_t); return __builtin_bit_cast(unsigned, b); }
; #define ATT_VLOAD(kk_, buf_) do { const unsigned r0_ = 32 * (ks0 + (kk_)) + 8 * kg + q4; _Pragma("unroll") for (int c = 0; c < 8; ++c) { \
;         vlo[buf_][c] = vtr(vbase + ((off_b(r0_, 2 * c + (p4 >> 1)) + 8 * (p4 & 1)) ^ par)); vhi[buf_][c] = vtr(vbase + ((off_b(r0_ + 4, 2 * c + (p4 >> 1)) + 8 * (p4 & 1)) ^ par)); } } while (0)
; __device__ __forceinline__ void attn_compute(LAS unsigned char* lds, const bf16x8 (&qf)[4], const AttnUnit& u, bf16* og, float* lse) {
;     ...
;     for (int kk = 0; kk < 5; ++kk) {
;         if (kk < 4) ATT_VLOAD(kk + 1, (kk + 1) & 1);
; #pragma unroll
;         for (int c = 0; c < 8; ++c) {
;             const s16x4 lo = vlo[kk & 1][c], hi = vhi[kk & 1][c];
;             const bf16x8 vf = (bf16x8){lo[0], lo[1], lo[2], lo[3], hi[0], hi[1], hi[2], hi[3]};
;             o[c] = __builtin_amdgcn_mfma_f32_16x16x32_bf16(vf, pf[kk], o[c], 0, 0, 0);
;         }
;     }
;     ...
;     const float rl = 1.0f / l;
;     bf16* op = og + qtok * 1024 + h * 128 + 4 * kg;
; #pragma unroll
;     for (int c = 0; c < 8; ++c) { v2u wv; wv.x = cvtpk(o[c][0] * rl, o[c][1] * rl); wv.y = cvtpk(o[c][2] * rl, o[c][3] * rl); *(v2u*)(op + 16 * c) = wv; }
;     if (kg == 0) lse[qtok * 8 + h] = mx + __builtin_amdgcn_logf(l);
	v_mfma_f32_16x16x32_bf16 v[60:63], v[60:63], v[48:51], v[64:67]
	v_mfma_f32_16x16x32_bf16 v[64:67], v[154:157], v[48:51], v[72:75]
	v_mfma_f32_16x16x32_bf16 v[72:75], v[158:161], v[48:51], v[86:89]
	s_nop 2
	ds_read_b64_tr_b16 v[86:87], v71
	v_bitop3_b32 v71, v83, v129, v113 bitop3:0x36
	v_lshlrev_b32_e32 v71, 4, v71
	v_bitop3_b32 v71, v71, s77, v85 bitop3:0x36
	v_add_u32_e32 v71, s73, v71
	ds_read_b64_tr_b16 v[88:89], v71
	s_waitcnt lgkmcnt(5)
	v_mfma_f32_16x16x32_bf16 v[76:79], v[76:79], v[48:51], v[134:137]
	v_mov_b32_e32 v85, v81
	v_mfma_f32_16x16x32_bf16 v[134:137], v[162:165], v[48:51], v[138:141]
	s_waitcnt lgkmcnt(4)
	v_mfma_f32_16x16x32_bf16 v[138:141], v[150:153], v[48:51], v[142:145]
	v_lshlrev_b64 v[150:151], s8, v[80:81]
	s_lshl_b32 s8, s76, 8
	s_waitcnt lgkmcnt(2)
	v_mfma_f32_16x16x32_bf16 v[142:145], v[52:55], v[48:51], v[146:149]
	v_add_f32_e32 v54, v69, v70
	v_div_scale_f32 v55, s[30:31], v54, v54, 1.0
	v_rcp_f32_e32 v69, v55
	s_waitcnt lgkmcnt(0)
	v_mfma_f32_16x16x32_bf16 v[48:51], v[86:89], v[48:51], v[56:59]
	v_lshl_add_u64 v[52:53], s[62:63], 0, v[150:151]
	s_nop 1
	v_fma_f32 v56, -v55, v69, 1.0
	v_fmac_f32_e32 v69, v56, v69
	v_div_scale_f32 v56, vcc, 1.0, v54, 1.0
	v_mul_f32_e32 v57, v56, v69
	v_fma_f32 v58, -v55, v57, v56
	v_fmac_f32_e32 v57, v58, v69
	v_fma_f32 v55, -v55, v57, v56
	v_div_fmas_f32 v55, v55, v69, v57
	v_lshlrev_b64 v[58:59], 11, v[52:53]
	v_div_fixup_f32 v56, v55, v54, 1.0
	v_lshl_add_u64 v[58:59], s[60:61], 0, v[58:59]
	v_lshl_add_u64 v[58:59], v[58:59], 0, s[8:9]
	v_pk_mul_f32 v[60:61], v[56:57], v[60:61] op_sel_hi:[0,1]
	v_pk_mul_f32 v[62:63], v[56:57], v[62:63] op_sel_hi:[0,1]
	v_lshl_add_u64 v[58:59], v[58:59], 0, v[84:85]
	v_cvt_pk_bf16_f32 v60, v60, v61
	v_cvt_pk_bf16_f32 v61, v62, v63
	global_store_dwordx2 v[58:59], v[60:61], off
	v_pk_mul_f32 v[60:61], v[56:57], v[64:65] op_sel_hi:[0,1]
	v_pk_mul_f32 v[62:63], v[56:57], v[66:67] op_sel_hi:[0,1]
	v_cvt_pk_bf16_f32 v60, v60, v61
	v_cvt_pk_bf16_f32 v61, v62, v63
	global_store_dwordx2 v[58:59], v[60:61], off offset:32
	v_pk_mul_f32 v[60:61], v[56:57], v[72:73] op_sel_hi:[0,1]
	v_pk_mul_f32 v[62:63], v[56:57], v[74:75] op_sel_hi:[0,1]
	v_cvt_pk_bf16_f32 v60, v60, v61
	v_cvt_pk_bf16_f32 v61, v62, v63
	global_store_dwordx2 v[58:59], v[60:61], off offset:64
	v_pk_mul_f32 v[60:61], v[56:57], v[76:77] op_sel_hi:[0,1]
	v_pk_mul_f32 v[62:63], v[56:57], v[78:79] op_sel_hi:[0,1]
	v_cvt_pk_bf16_f32 v60, v60, v61
	v_cvt_pk_bf16_f32 v61, v62, v63
	global_store_dwordx2 v[58:59], v[60:61], off offset:96
	v_pk_mul_f32 v[60:61], v[56:57], v[134:135] op_sel_hi:[0,1]
	v_pk_mul_f32 v[62:63], v[56:57], v[136:137] op_sel_hi:[0,1]
	v_cvt_pk_bf16_f32 v60, v60, v61
	v_cvt_pk_bf16_f32 v61, v62, v63
	global_store_dwordx2 v[58:59], v[60:61], off offset:128
	v_pk_mul_f32 v[60:61], v[56:57], v[138:139] op_sel_hi:[0,1]
	v_pk_mul_f32 v[62:63], v[56:57], v[140:141] op_sel_hi:[0,1]
	v_cvt_pk_bf16_f32 v60, v60, v61
	v_cvt_pk_bf16_f32 v61, v62, v63
	global_store_dwordx2 v[58:59], v[60:61], off offset:160
	v_pk_mul_f32 v[60:61], v[56:57], v[142:143] op_sel_hi:[0,1]
	v_pk_mul_f32 v[62:63], v[56:57], v[144:145] op_sel_hi:[0,1]
	v_pk_mul_f32 v[48:49], v[56:57], v[48:49] op_sel_hi:[0,1]
	v_pk_mul_f32 v[50:51], v[56:57], v[50:51] op_sel_hi:[0,1]
	v_cvt_pk_bf16_f32 v60, v60, v61
	v_cvt_pk_bf16_f32 v61, v62, v63
	v_cvt_pk_bf16_f32 v48, v48, v49
	v_cvt_pk_bf16_f32 v49, v50, v51
	global_store_dwordx2 v[58:59], v[60:61], off offset:192
	global_store_dwordx2 v[58:59], v[48:49], off offset:224
	s_and_saveexec_b64 s[60:61], s[6:7]
	s_cbranch_execz .LBB0_146
	v_log_f32_e32 v48, v54
	s_ashr_i32 s11, s10, 31
	s_lshl_b64 s[10:11], s[10:11], 20
	s_add_u32 s10, s0, s10
	v_add_f32_e32 v50, v68, v48
	s_addc_u32 s11, s1, s11
	v_lshlrev_b64 v[48:49], 5, v[52:53]
	v_lshl_add_u64 v[48:49], s[10:11], 0, v[48:49]
	s_lshl_b32 s8, s76, 2
	v_lshl_add_u64 v[48:49], v[48:49], 0, s[8:9]
	global_store_dword v[48:49], v50, off
	s_branch .LBB0_146
